# residual epilogues write the bf16 copy with dwordx4 stores (v_permlane16_swap pairs adjacent lane rows): half the bf16 store requests
# speedup vs baseline: 1.0175x; 1.0030x over previous
.LBB0_359:
	v_bfe_u32 v182, v208, 4, 1
	v_mul_u32_u24_e32 v182, 24, v182
	v_mov_b32_e32 v183, 0
	v_lshl_add_u32 v166, s10, 8, v176
	v_lshl_or_b32 v164, s9, 8, v178
	v_ashrrev_i32_e32 v167, 31, v166
	v_or_b32_e32 v168, 16, v166
	v_lshlrev_b64 v[130:131], 11, v[166:167]
	v_ashrrev_i32_e32 v165, 31, v164
	v_ashrrev_i32_e32 v169, 31, v168
	v_lshlrev_b64 v[132:133], 13, v[166:167]
	v_lshl_add_u64 v[180:181], v[130:131], 0, v[164:165]
	v_lshlrev_b64 v[130:131], 13, v[168:169]
	v_lshl_add_u64 v[132:133], s[54:55], 0, v[132:133]
	v_lshlrev_b64 v[134:135], 2, v[164:165]
	v_lshl_add_u64 v[130:131], s[54:55], 0, v[130:131]
	v_lshl_add_u64 v[132:133], v[132:133], 0, v[134:135]
	v_lshl_add_u64 v[130:131], v[130:131], 0, v[134:135]
	global_load_dwordx4 v[170:173], v[132:133], off
	global_load_dwordx4 v[154:157], v[132:133], off offset:64
	global_load_dwordx4 v[150:153], v[132:133], off offset:512
	global_load_dwordx4 v[146:149], v[132:133], off offset:576
	global_load_dwordx4 v[142:145], v[130:131], off
	global_load_dwordx4 v[138:141], v[130:131], off offset:64
	global_load_dwordx4 v[134:137], v[130:131], off offset:512
	s_nop 0
	global_load_dwordx4 v[130:133], v[130:131], off offset:576
	v_lshl_add_u64 v[174:175], v[180:181], 2, s[94:95]
	s_and_b64 vcc, exec, s[86:87]
	s_waitcnt vmcnt(0)
	v_pk_add_f32 v[128:129], v[128:129], v[172:173]
	v_pk_add_f32 v[126:127], v[126:127], v[170:171]
	v_lshl_add_u64 v[172:173], v[180:181], 1, s[16:17]
	global_store_dwordx4 v[174:175], v[126:129], off
	s_cbranch_vccz .LBB0_361
	v_cvt_pk_bf16_f32 v184, v126, v127
	v_cvt_pk_bf16_f32 v185, v128, v129
.LBB0_361:
	v_lshlrev_b64 v[170:171], 11, v[168:169]
	v_pk_add_f32 v[124:125], v[124:125], v[156:157]
	v_pk_add_f32 v[122:123], v[122:123], v[154:155]
	s_and_b64 vcc, exec, s[86:87]
	global_store_dwordx4 v[174:175], v[122:125], off offset:64
	s_cbranch_vccz .LBB0_363
	v_cvt_pk_bf16_f32 v186, v122, v123
	v_cvt_pk_bf16_f32 v187, v124, v125
	s_nop 1
	v_permlane16_swap_b32_e32 v184, v186
	v_permlane16_swap_b32_e32 v185, v187
	v_lshl_add_u64 v[172:173], v[172:173], 0, v[182:183]
	global_store_dwordx4 v[172:173], v[184:187], off
.LBB0_363:
	v_pk_add_f32 v[120:121], v[120:121], v[152:153]
	v_pk_add_f32 v[118:119], v[118:119], v[150:151]
	s_and_b64 vcc, exec, s[86:87]
	global_store_dwordx4 v[174:175], v[118:121], off offset:512
	s_cbranch_vccz .LBB0_365
	v_cvt_pk_bf16_f32 v188, v118, v119
	v_cvt_pk_bf16_f32 v189, v120, v121
.LBB0_365:
	v_pk_add_f32 v[114:115], v[114:115], v[146:147]
	v_cndmask_b32_e64 v146, 0, 1, s[86:87]
	v_pk_add_f32 v[116:117], v[116:117], v[148:149]
	v_cmp_ne_u32_e64 s[46:47], 1, v146
	s_andn2_b64 vcc, exec, s[86:87]
	global_store_dwordx4 v[174:175], v[114:117], off offset:576
	s_cbranch_vccnz .LBB0_369
	v_mul_f32_e32 v127, v127, v127
	v_mul_f32_e32 v123, v123, v123
	v_mul_f32_e32 v119, v119, v119
	v_fmac_f32_e32 v127, v126, v126
	v_mul_f32_e32 v126, v128, v128
	v_fmac_f32_e32 v123, v122, v122
	v_mul_f32_e32 v122, v124, v124
	v_fmac_f32_e32 v119, v118, v118
	v_mul_f32_e32 v118, v120, v120
	v_fmac_f32_e32 v126, v129, v129
	v_fmac_f32_e32 v122, v125, v125
	v_fmac_f32_e32 v118, v121, v121
	v_add_f32_e32 v126, v127, v126
	v_add_f32_e32 v122, v123, v122
	v_add_f32_e32 v118, v119, v118
	v_mul_f32_e32 v119, v115, v115
	v_mul_f32_e32 v120, v117, v117
	v_add_f32_e32 v122, v126, v122
	v_fmac_f32_e32 v119, v114, v114
	v_fmac_f32_e32 v120, v116, v116
	v_add_f32_e32 v118, v122, v118
	v_add_f32_e32 v119, v119, v120
	v_add_f32_e32 v118, v119, v118
	ds_swizzle_b32 v119, v118 offset:swizzle(SWAP,16)
	v_cvt_pk_bf16_f32 v190, v114, v115
	v_cvt_pk_bf16_f32 v191, v116, v117
	s_nop 1
	v_permlane16_swap_b32_e32 v188, v190
	v_permlane16_swap_b32_e32 v189, v191
	global_store_dwordx4 v[172:173], v[188:191], off offset:256
	s_waitcnt lgkmcnt(0)
	v_add_f32_e32 v114, v118, v119
	v_mov_b32_e32 v115, v114
	s_nop 1
	v_permlane32_swap_b32_e32 v114, v115
	s_and_saveexec_b64 s[66:67], s[40:41]
	s_cbranch_execz .LBB0_368
	v_add_f32_e32 v116, v114, v115
	s_lshl_b32 s10, s9, 2
	v_lshlrev_b64 v[114:115], 7, v[166:167]
	s_ashr_i32 s11, s10, 31
	v_lshl_add_u64 v[114:115], s[0:1], 0, v[114:115]
	v_lshl_add_u64 v[114:115], s[10:11], 2, v[114:115]
	s_lshl_b32 s84, s22, 2
	v_lshl_add_u64 v[114:115], v[114:115], 0, s[84:85]
	global_store_dword v[114:115], v116, off

.LBB0_369:
	v_or_b32_e32 v146, 32, v166
	v_ashrrev_i32_e32 v147, 31, v146
	v_lshlrev_b64 v[114:115], 13, v[146:147]
	v_lshl_add_u64 v[114:115], s[54:55], 0, v[114:115]
	v_lshl_add_u64 v[114:115], v[164:165], 2, v[114:115]
	global_load_dwordx4 v[126:129], v[114:115], off
	global_load_dwordx4 v[122:125], v[114:115], off offset:64
	global_load_dwordx4 v[118:121], v[114:115], off offset:512
	s_nop 0
	global_load_dwordx4 v[114:117], v[114:115], off offset:576
	v_lshl_add_u64 v[150:151], v[170:171], 0, v[164:165]
	v_pk_add_f32 v[112:113], v[112:113], v[144:145]
	v_pk_add_f32 v[110:111], v[110:111], v[142:143]
	v_lshl_add_u64 v[148:149], v[150:151], 2, s[94:95]
	s_and_b64 vcc, exec, s[86:87]
	v_lshl_add_u64 v[144:145], v[150:151], 1, s[16:17]
	global_store_dwordx4 v[148:149], v[110:113], off
	s_cbranch_vccz .LBB0_371
	v_cvt_pk_bf16_f32 v184, v110, v111
	v_cvt_pk_bf16_f32 v185, v112, v113
.LBB0_371:
	v_lshlrev_b64 v[142:143], 11, v[146:147]
	v_pk_add_f32 v[108:109], v[108:109], v[140:141]
	v_pk_add_f32 v[106:107], v[106:107], v[138:139]
	s_and_b64 vcc, exec, s[86:87]
	global_store_dwordx4 v[148:149], v[106:109], off offset:64
	s_cbranch_vccz .LBB0_373
	v_cvt_pk_bf16_f32 v186, v106, v107
	v_cvt_pk_bf16_f32 v187, v108, v109
	s_nop 1
	v_permlane16_swap_b32_e32 v184, v186
	v_permlane16_swap_b32_e32 v185, v187
	v_lshl_add_u64 v[144:145], v[144:145], 0, v[182:183]
	global_store_dwordx4 v[144:145], v[184:187], off
.LBB0_373:
	v_pk_add_f32 v[104:105], v[104:105], v[136:137]
	v_pk_add_f32 v[102:103], v[102:103], v[134:135]
	s_and_b64 vcc, exec, s[86:87]
	global_store_dwordx4 v[148:149], v[102:105], off offset:512
	s_cbranch_vccz .LBB0_375
	v_cvt_pk_bf16_f32 v188, v102, v103
	v_cvt_pk_bf16_f32 v189, v104, v105
.LBB0_375:
	v_pk_add_f32 v[100:101], v[100:101], v[132:133]
	v_pk_add_f32 v[98:99], v[98:99], v[130:131]
	s_and_b64 vcc, exec, s[46:47]
	global_store_dwordx4 v[148:149], v[98:101], off offset:576
	s_cbranch_vccnz .LBB0_379
	v_mul_f32_e32 v111, v111, v111
	v_mul_f32_e32 v107, v107, v107
	v_mul_f32_e32 v103, v103, v103
	v_fmac_f32_e32 v111, v110, v110
	v_mul_f32_e32 v110, v112, v112
	v_fmac_f32_e32 v107, v106, v106
	v_mul_f32_e32 v106, v108, v108
	v_fmac_f32_e32 v103, v102, v102
	v_mul_f32_e32 v102, v104, v104
	v_fmac_f32_e32 v110, v113, v113
	v_fmac_f32_e32 v106, v109, v109
	v_fmac_f32_e32 v102, v105, v105
	v_add_f32_e32 v110, v111, v110
	v_add_f32_e32 v106, v107, v106
	v_add_f32_e32 v102, v103, v102
	v_mul_f32_e32 v103, v99, v99
	v_mul_f32_e32 v104, v101, v101
	v_add_f32_e32 v106, v110, v106
	v_fmac_f32_e32 v103, v98, v98
	v_fmac_f32_e32 v104, v100, v100
	v_add_f32_e32 v102, v106, v102
	v_add_f32_e32 v103, v103, v104
	v_add_f32_e32 v102, v103, v102
	ds_swizzle_b32 v103, v102 offset:swizzle(SWAP,16)
	v_cvt_pk_bf16_f32 v190, v98, v99
	v_cvt_pk_bf16_f32 v191, v100, v101
	s_nop 1
	v_permlane16_swap_b32_e32 v188, v190
	v_permlane16_swap_b32_e32 v189, v191
	global_store_dwordx4 v[144:145], v[188:191], off offset:256
	s_waitcnt lgkmcnt(0)
	v_add_f32_e32 v98, v102, v103
	v_mov_b32_e32 v99, v98
	s_nop 1
	v_permlane32_swap_b32_e32 v98, v99
	s_and_saveexec_b64 s[66:67], s[40:41]
	s_cbranch_execz .LBB0_378
	v_add_f32_e32 v100, v98, v99
	s_lshl_b32 s10, s9, 2
	v_lshlrev_b64 v[98:99], 7, v[168:169]
	s_ashr_i32 s11, s10, 31
	v_lshl_add_u64 v[98:99], s[0:1], 0, v[98:99]
	v_lshl_add_u64 v[98:99], s[10:11], 2, v[98:99]
	s_lshl_b32 s84, s22, 2
	v_lshl_add_u64 v[98:99], v[98:99], 0, s[84:85]
	global_store_dword v[98:99], v100, off

.LBB0_379:
	v_or_b32_e32 v130, 48, v166
	v_ashrrev_i32_e32 v131, 31, v130
	v_lshlrev_b64 v[98:99], 13, v[130:131]
	v_lshl_add_u64 v[98:99], s[54:55], 0, v[98:99]
	v_lshl_add_u64 v[98:99], v[164:165], 2, v[98:99]
	global_load_dwordx4 v[110:113], v[98:99], off
	global_load_dwordx4 v[106:109], v[98:99], off offset:64
	global_load_dwordx4 v[102:105], v[98:99], off offset:512
	s_nop 0
	global_load_dwordx4 v[98:101], v[98:99], off offset:576
	v_lshl_add_u64 v[134:135], v[142:143], 0, v[164:165]
	s_waitcnt vmcnt(11)
	v_pk_add_f32 v[96:97], v[96:97], v[128:129]
	v_pk_add_f32 v[94:95], v[94:95], v[126:127]
	v_lshl_add_u64 v[132:133], v[134:135], 2, s[94:95]
	s_and_b64 vcc, exec, s[86:87]
	v_lshl_add_u64 v[128:129], v[134:135], 1, s[16:17]
	global_store_dwordx4 v[132:133], v[94:97], off
	s_cbranch_vccz .LBB0_381
	v_cvt_pk_bf16_f32 v184, v94, v95
	v_cvt_pk_bf16_f32 v185, v96, v97
.LBB0_381:
	v_lshlrev_b64 v[126:127], 11, v[130:131]
	s_waitcnt vmcnt(11)
	v_pk_add_f32 v[92:93], v[92:93], v[124:125]
	v_pk_add_f32 v[90:91], v[90:91], v[122:123]
	s_and_b64 vcc, exec, s[86:87]
	global_store_dwordx4 v[132:133], v[90:93], off offset:64
	s_cbranch_vccz .LBB0_383
	v_cvt_pk_bf16_f32 v186, v90, v91
	v_cvt_pk_bf16_f32 v187, v92, v93
	s_nop 1
	v_permlane16_swap_b32_e32 v184, v186
	v_permlane16_swap_b32_e32 v185, v187
	v_lshl_add_u64 v[128:129], v[128:129], 0, v[182:183]
	global_store_dwordx4 v[128:129], v[184:187], off
.LBB0_383:
	s_waitcnt vmcnt(11)
	v_pk_add_f32 v[88:89], v[88:89], v[120:121]
	v_pk_add_f32 v[86:87], v[86:87], v[118:119]
	s_and_b64 vcc, exec, s[86:87]
	global_store_dwordx4 v[132:133], v[86:89], off offset:512
	s_cbranch_vccz .LBB0_385
	v_cvt_pk_bf16_f32 v188, v86, v87
	v_cvt_pk_bf16_f32 v189, v88, v89
.LBB0_385:
	s_waitcnt vmcnt(11)
	v_pk_add_f32 v[84:85], v[84:85], v[116:117]
	v_pk_add_f32 v[82:83], v[82:83], v[114:115]
	s_and_b64 vcc, exec, s[46:47]
	global_store_dwordx4 v[132:133], v[82:85], off offset:576
	s_cbranch_vccnz .LBB0_389
	v_mul_f32_e32 v95, v95, v95
	v_mul_f32_e32 v91, v91, v91
	v_mul_f32_e32 v87, v87, v87
	v_fmac_f32_e32 v95, v94, v94
	v_mul_f32_e32 v94, v96, v96
	v_fmac_f32_e32 v91, v90, v90
	v_mul_f32_e32 v90, v92, v92
	v_fmac_f32_e32 v87, v86, v86
	v_mul_f32_e32 v86, v88, v88
	v_fmac_f32_e32 v94, v97, v97
	v_fmac_f32_e32 v90, v93, v93
	v_fmac_f32_e32 v86, v89, v89
	v_add_f32_e32 v94, v95, v94
	v_add_f32_e32 v90, v91, v90
	v_add_f32_e32 v86, v87, v86
	v_mul_f32_e32 v87, v83, v83
	v_mul_f32_e32 v88, v85, v85
	v_add_f32_e32 v90, v94, v90
	v_fmac_f32_e32 v87, v82, v82
	v_fmac_f32_e32 v88, v84, v84
	v_add_f32_e32 v86, v90, v86
	v_add_f32_e32 v87, v87, v88
	v_add_f32_e32 v86, v87, v86
	ds_swizzle_b32 v87, v86 offset:swizzle(SWAP,16)
	v_cvt_pk_bf16_f32 v190, v82, v83
	v_cvt_pk_bf16_f32 v191, v84, v85
	s_nop 1
	v_permlane16_swap_b32_e32 v188, v190
	v_permlane16_swap_b32_e32 v189, v191
	global_store_dwordx4 v[128:129], v[188:191], off offset:256
	s_waitcnt lgkmcnt(0)
	v_add_f32_e32 v82, v86, v87
	v_mov_b32_e32 v83, v82
	s_nop 1
	v_permlane32_swap_b32_e32 v82, v83
	s_and_saveexec_b64 s[66:67], s[40:41]
	s_cbranch_execz .LBB0_388
	v_add_f32_e32 v84, v82, v83
	s_lshl_b32 s10, s9, 2
	v_lshlrev_b64 v[82:83], 7, v[146:147]
	s_ashr_i32 s11, s10, 31
	v_lshl_add_u64 v[82:83], s[0:1], 0, v[82:83]
	v_lshl_add_u64 v[82:83], s[10:11], 2, v[82:83]
	s_lshl_b32 s84, s22, 2
	v_lshl_add_u64 v[82:83], v[82:83], 0, s[84:85]
	global_store_dword v[82:83], v84, off

.LBB0_389:
	v_add_u32_e32 v114, 0x80, v166
	v_ashrrev_i32_e32 v115, 31, v114
	v_lshlrev_b64 v[82:83], 13, v[114:115]
	v_lshl_add_u64 v[82:83], s[54:55], 0, v[82:83]
	v_lshl_add_u64 v[82:83], v[164:165], 2, v[82:83]
	global_load_dwordx4 v[94:97], v[82:83], off
	global_load_dwordx4 v[90:93], v[82:83], off offset:64
	global_load_dwordx4 v[86:89], v[82:83], off offset:512
	s_nop 0
	global_load_dwordx4 v[82:85], v[82:83], off offset:576
	v_lshl_add_u64 v[118:119], v[126:127], 0, v[164:165]
	s_waitcnt vmcnt(11)
	v_pk_add_f32 v[80:81], v[80:81], v[112:113]
	v_pk_add_f32 v[78:79], v[78:79], v[110:111]
	v_lshl_add_u64 v[116:117], v[118:119], 2, s[94:95]
	s_and_b64 vcc, exec, s[86:87]
	v_lshl_add_u64 v[112:113], v[118:119], 1, s[16:17]
	global_store_dwordx4 v[116:117], v[78:81], off
	s_cbranch_vccz .LBB0_391
	v_cvt_pk_bf16_f32 v184, v78, v79
	v_cvt_pk_bf16_f32 v185, v80, v81
.LBB0_391:
	v_lshlrev_b64 v[110:111], 11, v[114:115]
	s_waitcnt vmcnt(11)
	v_pk_add_f32 v[76:77], v[76:77], v[108:109]
	v_pk_add_f32 v[74:75], v[74:75], v[106:107]
	s_and_b64 vcc, exec, s[86:87]
	global_store_dwordx4 v[116:117], v[74:77], off offset:64
	s_cbranch_vccz .LBB0_393
	v_cvt_pk_bf16_f32 v186, v74, v75
	v_cvt_pk_bf16_f32 v187, v76, v77
	s_nop 1
	v_permlane16_swap_b32_e32 v184, v186
	v_permlane16_swap_b32_e32 v185, v187
	v_lshl_add_u64 v[112:113], v[112:113], 0, v[182:183]
	global_store_dwordx4 v[112:113], v[184:187], off
.LBB0_393:
	s_waitcnt vmcnt(11)
	v_pk_add_f32 v[72:73], v[72:73], v[104:105]
	v_pk_add_f32 v[70:71], v[70:71], v[102:103]
	s_and_b64 vcc, exec, s[86:87]
	global_store_dwordx4 v[116:117], v[70:73], off offset:512
	s_cbranch_vccz .LBB0_395
	v_cvt_pk_bf16_f32 v188, v70, v71
	v_cvt_pk_bf16_f32 v189, v72, v73
.LBB0_395:
	s_waitcnt vmcnt(11)
	v_pk_add_f32 v[68:69], v[68:69], v[100:101]
	v_pk_add_f32 v[66:67], v[66:67], v[98:99]
	s_and_b64 vcc, exec, s[46:47]
	global_store_dwordx4 v[116:117], v[66:69], off offset:576
	s_cbranch_vccnz .LBB0_399
	v_mul_f32_e32 v79, v79, v79
	v_mul_f32_e32 v75, v75, v75
	v_mul_f32_e32 v71, v71, v71
	v_fmac_f32_e32 v79, v78, v78
	v_mul_f32_e32 v78, v80, v80
	v_fmac_f32_e32 v75, v74, v74
	v_mul_f32_e32 v74, v76, v76
	v_fmac_f32_e32 v71, v70, v70
	v_mul_f32_e32 v70, v72, v72
	v_fmac_f32_e32 v78, v81, v81
	v_fmac_f32_e32 v74, v77, v77
	v_fmac_f32_e32 v70, v73, v73
	v_add_f32_e32 v78, v79, v78
	v_add_f32_e32 v74, v75, v74
	v_add_f32_e32 v70, v71, v70
	v_mul_f32_e32 v71, v67, v67
	v_mul_f32_e32 v72, v69, v69
	v_add_f32_e32 v74, v78, v74
	v_fmac_f32_e32 v71, v66, v66
	v_fmac_f32_e32 v72, v68, v68
	v_add_f32_e32 v70, v74, v70
	v_add_f32_e32 v71, v71, v72
	v_add_f32_e32 v70, v71, v70
	ds_swizzle_b32 v71, v70 offset:swizzle(SWAP,16)
	v_cvt_pk_bf16_f32 v190, v66, v67
	v_cvt_pk_bf16_f32 v191, v68, v69
	s_nop 1
	v_permlane16_swap_b32_e32 v188, v190
	v_permlane16_swap_b32_e32 v189, v191
	global_store_dwordx4 v[112:113], v[188:191], off offset:256
	s_waitcnt lgkmcnt(0)
	v_add_f32_e32 v66, v70, v71
	v_mov_b32_e32 v67, v66
	s_nop 1
	v_permlane32_swap_b32_e32 v66, v67
	s_and_saveexec_b64 s[66:67], s[40:41]
	s_cbranch_execz .LBB0_398
	v_add_f32_e32 v68, v66, v67
	s_lshl_b32 s10, s9, 2
	v_lshlrev_b64 v[66:67], 7, v[130:131]
	s_ashr_i32 s11, s10, 31
	v_lshl_add_u64 v[66:67], s[0:1], 0, v[66:67]
	v_lshl_add_u64 v[66:67], s[10:11], 2, v[66:67]
	s_lshl_b32 s84, s22, 2
	v_lshl_add_u64 v[66:67], v[66:67], 0, s[84:85]
	global_store_dword v[66:67], v68, off

.LBB0_399:
	v_or_b32_e32 v98, 16, v114
	v_ashrrev_i32_e32 v99, 31, v98
	v_lshlrev_b64 v[66:67], 13, v[98:99]
	v_lshl_add_u64 v[66:67], s[54:55], 0, v[66:67]
	v_lshl_add_u64 v[66:67], v[164:165], 2, v[66:67]
	global_load_dwordx4 v[78:81], v[66:67], off
	global_load_dwordx4 v[74:77], v[66:67], off offset:64
	global_load_dwordx4 v[70:73], v[66:67], off offset:512
	s_nop 0
	global_load_dwordx4 v[66:69], v[66:67], off offset:576
	v_lshl_add_u64 v[102:103], v[110:111], 0, v[164:165]
	s_waitcnt vmcnt(11)
	v_pk_add_f32 v[64:65], v[64:65], v[96:97]
	v_pk_add_f32 v[62:63], v[62:63], v[94:95]
	v_lshl_add_u64 v[100:101], v[102:103], 2, s[94:95]
	s_and_b64 vcc, exec, s[86:87]
	v_lshl_add_u64 v[96:97], v[102:103], 1, s[16:17]
	global_store_dwordx4 v[100:101], v[62:65], off
	s_cbranch_vccz .LBB0_401
	v_cvt_pk_bf16_f32 v184, v62, v63
	v_cvt_pk_bf16_f32 v185, v64, v65
.LBB0_401:
	v_lshlrev_b64 v[94:95], 11, v[98:99]
	s_waitcnt vmcnt(11)
	v_pk_add_f32 v[60:61], v[60:61], v[92:93]
	v_pk_add_f32 v[58:59], v[58:59], v[90:91]
	s_and_b64 vcc, exec, s[86:87]
	global_store_dwordx4 v[100:101], v[58:61], off offset:64
	s_cbranch_vccz .LBB0_403
	v_cvt_pk_bf16_f32 v186, v58, v59
	v_cvt_pk_bf16_f32 v187, v60, v61
	s_nop 1
	v_permlane16_swap_b32_e32 v184, v186
	v_permlane16_swap_b32_e32 v185, v187
	v_lshl_add_u64 v[96:97], v[96:97], 0, v[182:183]
	global_store_dwordx4 v[96:97], v[184:187], off
.LBB0_403:
	s_waitcnt vmcnt(11)
	v_pk_add_f32 v[56:57], v[56:57], v[88:89]
	v_pk_add_f32 v[54:55], v[54:55], v[86:87]
	s_and_b64 vcc, exec, s[86:87]
	global_store_dwordx4 v[100:101], v[54:57], off offset:512
	s_cbranch_vccz .LBB0_405
	v_cvt_pk_bf16_f32 v188, v54, v55
	v_cvt_pk_bf16_f32 v189, v56, v57
.LBB0_405:
	s_waitcnt vmcnt(11)
	v_pk_add_f32 v[52:53], v[52:53], v[84:85]
	v_pk_add_f32 v[50:51], v[50:51], v[82:83]
	s_and_b64 vcc, exec, s[46:47]
	global_store_dwordx4 v[100:101], v[50:53], off offset:576
	s_cbranch_vccnz .LBB0_409
	v_mul_f32_e32 v63, v63, v63
	v_mul_f32_e32 v59, v59, v59
	v_mul_f32_e32 v55, v55, v55
	v_fmac_f32_e32 v63, v62, v62
	v_mul_f32_e32 v62, v64, v64
	v_fmac_f32_e32 v59, v58, v58
	v_mul_f32_e32 v58, v60, v60
	v_fmac_f32_e32 v55, v54, v54
	v_mul_f32_e32 v54, v56, v56
	v_fmac_f32_e32 v62, v65, v65
	v_fmac_f32_e32 v58, v61, v61
	v_fmac_f32_e32 v54, v57, v57
	v_add_f32_e32 v62, v63, v62
	v_add_f32_e32 v58, v59, v58
	v_add_f32_e32 v54, v55, v54
	v_mul_f32_e32 v55, v51, v51
	v_mul_f32_e32 v56, v53, v53
	v_add_f32_e32 v58, v62, v58
	v_fmac_f32_e32 v55, v50, v50
	v_fmac_f32_e32 v56, v52, v52
	v_add_f32_e32 v54, v58, v54
	v_add_f32_e32 v55, v55, v56
	v_add_f32_e32 v54, v55, v54
	ds_swizzle_b32 v55, v54 offset:swizzle(SWAP,16)
	v_cvt_pk_bf16_f32 v190, v50, v51
	v_cvt_pk_bf16_f32 v191, v52, v53
	s_nop 1
	v_permlane16_swap_b32_e32 v188, v190
	v_permlane16_swap_b32_e32 v189, v191
	global_store_dwordx4 v[96:97], v[188:191], off offset:256
	s_waitcnt lgkmcnt(0)
	v_add_f32_e32 v50, v54, v55
	v_mov_b32_e32 v51, v50
	s_nop 1
	v_permlane32_swap_b32_e32 v50, v51
	s_and_saveexec_b64 s[66:67], s[40:41]
	s_cbranch_execz .LBB0_408
	v_add_f32_e32 v52, v50, v51
	s_lshl_b32 s10, s9, 2
	v_lshlrev_b64 v[50:51], 7, v[114:115]
	s_ashr_i32 s11, s10, 31
	v_lshl_add_u64 v[50:51], s[0:1], 0, v[50:51]
	v_lshl_add_u64 v[50:51], s[10:11], 2, v[50:51]
	s_lshl_b32 s84, s22, 2
	v_lshl_add_u64 v[50:51], v[50:51], 0, s[84:85]
	global_store_dword v[50:51], v52, off

.LBB0_409:
	v_or_b32_e32 v82, 32, v114
	v_ashrrev_i32_e32 v83, 31, v82
	v_lshlrev_b64 v[50:51], 13, v[82:83]
	v_lshl_add_u64 v[50:51], s[54:55], 0, v[50:51]
	v_lshl_add_u64 v[50:51], v[164:165], 2, v[50:51]
	global_load_dwordx4 v[62:65], v[50:51], off
	global_load_dwordx4 v[58:61], v[50:51], off offset:64
	global_load_dwordx4 v[54:57], v[50:51], off offset:512
	s_nop 0
	global_load_dwordx4 v[50:53], v[50:51], off offset:576
	v_lshl_add_u64 v[86:87], v[94:95], 0, v[164:165]
	s_waitcnt vmcnt(11)
	v_pk_add_f32 v[48:49], v[48:49], v[80:81]
	v_pk_add_f32 v[46:47], v[46:47], v[78:79]
	v_lshl_add_u64 v[84:85], v[86:87], 2, s[94:95]
	s_and_b64 vcc, exec, s[86:87]
	v_lshl_add_u64 v[80:81], v[86:87], 1, s[16:17]
	global_store_dwordx4 v[84:85], v[46:49], off
	s_cbranch_vccz .LBB0_411
	v_cvt_pk_bf16_f32 v184, v46, v47
	v_cvt_pk_bf16_f32 v185, v48, v49
.LBB0_411:
	v_lshlrev_b64 v[78:79], 11, v[82:83]
	s_waitcnt vmcnt(11)
	v_pk_add_f32 v[44:45], v[44:45], v[76:77]
	v_pk_add_f32 v[42:43], v[42:43], v[74:75]
	s_and_b64 vcc, exec, s[86:87]
	global_store_dwordx4 v[84:85], v[42:45], off offset:64
	s_cbranch_vccz .LBB0_413
	v_cvt_pk_bf16_f32 v186, v42, v43
	v_cvt_pk_bf16_f32 v187, v44, v45
	s_nop 1
	v_permlane16_swap_b32_e32 v184, v186
	v_permlane16_swap_b32_e32 v185, v187
	v_lshl_add_u64 v[80:81], v[80:81], 0, v[182:183]
	global_store_dwordx4 v[80:81], v[184:187], off
.LBB0_413:
	s_waitcnt vmcnt(11)
	v_pk_add_f32 v[40:41], v[40:41], v[72:73]
	v_pk_add_f32 v[38:39], v[38:39], v[70:71]
	s_and_b64 vcc, exec, s[86:87]
	global_store_dwordx4 v[84:85], v[38:41], off offset:512
	s_cbranch_vccz .LBB0_415
	v_cvt_pk_bf16_f32 v188, v38, v39
	v_cvt_pk_bf16_f32 v189, v40, v41
.LBB0_415:
	s_waitcnt vmcnt(11)
	v_pk_add_f32 v[36:37], v[36:37], v[68:69]
	v_pk_add_f32 v[34:35], v[34:35], v[66:67]
	s_and_b64 vcc, exec, s[46:47]
	global_store_dwordx4 v[84:85], v[34:37], off offset:576
	s_cbranch_vccnz .LBB0_419
	v_mul_f32_e32 v47, v47, v47
	v_mul_f32_e32 v43, v43, v43
	v_mul_f32_e32 v39, v39, v39
	v_fmac_f32_e32 v47, v46, v46
	v_mul_f32_e32 v46, v48, v48
	v_fmac_f32_e32 v43, v42, v42
	v_mul_f32_e32 v42, v44, v44
	v_fmac_f32_e32 v39, v38, v38
	v_mul_f32_e32 v38, v40, v40
	v_fmac_f32_e32 v46, v49, v49
	v_fmac_f32_e32 v42, v45, v45
	v_fmac_f32_e32 v38, v41, v41
	v_add_f32_e32 v46, v47, v46
	v_add_f32_e32 v42, v43, v42
	v_add_f32_e32 v38, v39, v38
	v_mul_f32_e32 v39, v35, v35
	v_mul_f32_e32 v40, v37, v37
	v_add_f32_e32 v42, v46, v42
	v_fmac_f32_e32 v39, v34, v34
	v_fmac_f32_e32 v40, v36, v36
	v_add_f32_e32 v38, v42, v38
	v_add_f32_e32 v39, v39, v40
	v_add_f32_e32 v38, v39, v38
	ds_swizzle_b32 v39, v38 offset:swizzle(SWAP,16)
	v_cvt_pk_bf16_f32 v190, v34, v35
	v_cvt_pk_bf16_f32 v191, v36, v37
	s_nop 1
	v_permlane16_swap_b32_e32 v188, v190
	v_permlane16_swap_b32_e32 v189, v191
	global_store_dwordx4 v[80:81], v[188:191], off offset:256
	s_waitcnt lgkmcnt(0)
	v_add_f32_e32 v34, v38, v39
	v_mov_b32_e32 v35, v34
	s_nop 1
	v_permlane32_swap_b32_e32 v34, v35
	s_and_saveexec_b64 s[66:67], s[40:41]
	s_cbranch_execz .LBB0_418
	v_add_f32_e32 v36, v34, v35
	s_lshl_b32 s10, s9, 2
	v_lshlrev_b64 v[34:35], 7, v[98:99]
	s_ashr_i32 s11, s10, 31
	v_lshl_add_u64 v[34:35], s[0:1], 0, v[34:35]
	v_lshl_add_u64 v[34:35], s[10:11], 2, v[34:35]
	s_lshl_b32 s84, s22, 2
	v_lshl_add_u64 v[34:35], v[34:35], 0, s[84:85]
	global_store_dword v[34:35], v36, off

.LBB0_419:
	v_or_b32_e32 v66, 48, v114
	v_ashrrev_i32_e32 v67, 31, v66
	v_lshlrev_b64 v[34:35], 13, v[66:67]
	v_lshl_add_u64 v[34:35], s[54:55], 0, v[34:35]
	v_lshl_add_u64 v[34:35], v[164:165], 2, v[34:35]
	global_load_dwordx4 v[46:49], v[34:35], off
	global_load_dwordx4 v[42:45], v[34:35], off offset:64
	global_load_dwordx4 v[38:41], v[34:35], off offset:512
	s_nop 0
	global_load_dwordx4 v[34:37], v[34:35], off offset:576
	v_lshl_add_u64 v[70:71], v[78:79], 0, v[164:165]
	s_waitcnt vmcnt(11)
	v_pk_add_f32 v[32:33], v[32:33], v[64:65]
	v_pk_add_f32 v[30:31], v[30:31], v[62:63]
	v_lshl_add_u64 v[68:69], v[70:71], 2, s[94:95]
	s_and_b64 vcc, exec, s[86:87]
	v_lshl_add_u64 v[64:65], v[70:71], 1, s[16:17]
	global_store_dwordx4 v[68:69], v[30:33], off
	s_cbranch_vccz .LBB0_421
	v_cvt_pk_bf16_f32 v184, v30, v31
	v_cvt_pk_bf16_f32 v185, v32, v33
.LBB0_421:
	v_lshlrev_b64 v[62:63], 11, v[66:67]
	s_waitcnt vmcnt(11)
	v_pk_add_f32 v[28:29], v[28:29], v[60:61]
	v_pk_add_f32 v[26:27], v[26:27], v[58:59]
	s_and_b64 vcc, exec, s[86:87]
	global_store_dwordx4 v[68:69], v[26:29], off offset:64
	s_cbranch_vccz .LBB0_423
	v_cvt_pk_bf16_f32 v186, v26, v27
	v_cvt_pk_bf16_f32 v187, v28, v29
	s_nop 1
	v_permlane16_swap_b32_e32 v184, v186
	v_permlane16_swap_b32_e32 v185, v187
	v_lshl_add_u64 v[64:65], v[64:65], 0, v[182:183]
	global_store_dwordx4 v[64:65], v[184:187], off
.LBB0_423:
	s_waitcnt vmcnt(11)
	v_pk_add_f32 v[24:25], v[24:25], v[56:57]
	v_pk_add_f32 v[22:23], v[22:23], v[54:55]
	s_and_b64 vcc, exec, s[86:87]
	global_store_dwordx4 v[68:69], v[22:25], off offset:512
	s_cbranch_vccz .LBB0_425
	v_cvt_pk_bf16_f32 v188, v22, v23
	v_cvt_pk_bf16_f32 v189, v24, v25
.LBB0_425:
	s_waitcnt vmcnt(11)
	v_pk_add_f32 v[20:21], v[20:21], v[52:53]
	v_pk_add_f32 v[18:19], v[18:19], v[50:51]
	s_and_b64 vcc, exec, s[46:47]
	global_store_dwordx4 v[68:69], v[18:21], off offset:576
	s_cbranch_vccnz .LBB0_429
	v_mul_f32_e32 v31, v31, v31
	v_mul_f32_e32 v27, v27, v27
	v_mul_f32_e32 v23, v23, v23
	v_fmac_f32_e32 v31, v30, v30
	v_mul_f32_e32 v30, v32, v32
	v_fmac_f32_e32 v27, v26, v26
	v_mul_f32_e32 v26, v28, v28
	v_fmac_f32_e32 v23, v22, v22
	v_mul_f32_e32 v22, v24, v24
	v_fmac_f32_e32 v30, v33, v33
	v_fmac_f32_e32 v26, v29, v29
	v_fmac_f32_e32 v22, v25, v25
	v_add_f32_e32 v30, v31, v30
	v_add_f32_e32 v26, v27, v26
	v_add_f32_e32 v22, v23, v22
	v_mul_f32_e32 v23, v19, v19
	v_mul_f32_e32 v24, v21, v21
	v_add_f32_e32 v26, v30, v26
	v_fmac_f32_e32 v23, v18, v18
	v_fmac_f32_e32 v24, v20, v20
	v_add_f32_e32 v22, v26, v22
	v_add_f32_e32 v23, v23, v24
	v_add_f32_e32 v22, v23, v22
	ds_swizzle_b32 v23, v22 offset:swizzle(SWAP,16)
	v_cvt_pk_bf16_f32 v190, v18, v19
	v_cvt_pk_bf16_f32 v191, v20, v21
	s_nop 1
	v_permlane16_swap_b32_e32 v188, v190
	v_permlane16_swap_b32_e32 v189, v191
	global_store_dwordx4 v[64:65], v[188:191], off offset:256
	s_waitcnt lgkmcnt(0)
	v_add_f32_e32 v18, v22, v23
	v_mov_b32_e32 v19, v18
	s_nop 1
	v_permlane32_swap_b32_e32 v18, v19
	s_and_saveexec_b64 s[66:67], s[40:41]
	s_cbranch_execz .LBB0_428
	v_add_f32_e32 v20, v18, v19
	s_lshl_b32 s10, s9, 2
	v_lshlrev_b64 v[18:19], 7, v[82:83]
	s_ashr_i32 s11, s10, 31
	v_lshl_add_u64 v[18:19], s[0:1], 0, v[18:19]
	v_lshl_add_u64 v[18:19], s[10:11], 2, v[18:19]
	s_lshl_b32 s84, s22, 2
	v_lshl_add_u64 v[18:19], v[18:19], 0, s[84:85]
	global_store_dword v[18:19], v20, off

.LBB0_429:
	s_nop 0
	v_lshl_add_u64 v[18:19], v[62:63], 0, v[164:165]
	s_waitcnt vmcnt(7)
	v_pk_add_f32 v[16:17], v[16:17], v[48:49]
	v_pk_add_f32 v[14:15], v[14:15], v[46:47]
	v_lshl_add_u64 v[20:21], v[18:19], 2, s[94:95]
	s_and_b64 vcc, exec, s[86:87]
	v_lshl_add_u64 v[18:19], v[18:19], 1, s[16:17]
	global_store_dwordx4 v[20:21], v[14:17], off
	s_cbranch_vccz .LBB0_431
	v_cvt_pk_bf16_f32 v184, v14, v15
	v_cvt_pk_bf16_f32 v185, v16, v17
.LBB0_431:
	s_waitcnt vmcnt(7)
	v_pk_add_f32 v[12:13], v[12:13], v[44:45]
	v_pk_add_f32 v[10:11], v[10:11], v[42:43]
	s_and_b64 vcc, exec, s[86:87]
	global_store_dwordx4 v[20:21], v[10:13], off offset:64
	s_cbranch_vccz .LBB0_433
	v_cvt_pk_bf16_f32 v186, v10, v11
	v_cvt_pk_bf16_f32 v187, v12, v13
	s_nop 1
	v_permlane16_swap_b32_e32 v184, v186
	v_permlane16_swap_b32_e32 v185, v187
	v_lshl_add_u64 v[18:19], v[18:19], 0, v[182:183]
	global_store_dwordx4 v[18:19], v[184:187], off
.LBB0_433:
	s_waitcnt vmcnt(7)
	v_pk_add_f32 v[8:9], v[8:9], v[40:41]
	v_pk_add_f32 v[6:7], v[6:7], v[38:39]
	s_and_b64 vcc, exec, s[86:87]
	global_store_dwordx4 v[20:21], v[6:9], off offset:512
	s_cbranch_vccz .LBB0_435
	v_cvt_pk_bf16_f32 v188, v6, v7
	v_cvt_pk_bf16_f32 v189, v8, v9
.LBB0_435:
	s_waitcnt vmcnt(7)
	v_pk_add_f32 v[4:5], v[4:5], v[36:37]
	v_pk_add_f32 v[2:3], v[2:3], v[34:35]
	s_and_b64 vcc, exec, s[46:47]
	global_store_dwordx4 v[20:21], v[2:5], off offset:576
	s_cbranch_vccnz .LBB0_439
	v_mul_f32_e32 v15, v15, v15
	v_mul_f32_e32 v11, v11, v11
	v_mul_f32_e32 v7, v7, v7
	v_fmac_f32_e32 v15, v14, v14
	v_mul_f32_e32 v14, v16, v16
	v_fmac_f32_e32 v11, v10, v10
	v_mul_f32_e32 v10, v12, v12
	v_fmac_f32_e32 v7, v6, v6
	v_mul_f32_e32 v6, v8, v8
	v_fmac_f32_e32 v14, v17, v17
	v_fmac_f32_e32 v10, v13, v13
	v_fmac_f32_e32 v6, v9, v9
	v_add_f32_e32 v14, v15, v14
	v_add_f32_e32 v10, v11, v10
	v_add_f32_e32 v6, v7, v6
	v_mul_f32_e32 v7, v3, v3
	v_mul_f32_e32 v8, v5, v5
	v_add_f32_e32 v10, v14, v10
	v_fmac_f32_e32 v7, v2, v2
	v_fmac_f32_e32 v8, v4, v4
	v_add_f32_e32 v6, v10, v6
	v_add_f32_e32 v7, v7, v8
	v_add_f32_e32 v6, v7, v6
	ds_swizzle_b32 v7, v6 offset:swizzle(SWAP,16)
	v_cvt_pk_bf16_f32 v190, v2, v3
	v_cvt_pk_bf16_f32 v191, v4, v5
	s_nop 1
	v_permlane16_swap_b32_e32 v188, v190
	v_permlane16_swap_b32_e32 v189, v191
	global_store_dwordx4 v[18:19], v[188:191], off offset:256
	s_waitcnt lgkmcnt(0)
	v_add_f32_e32 v2, v6, v7
	v_mov_b32_e32 v3, v2
	s_nop 1
	v_permlane32_swap_b32_e32 v2, v3
	s_and_saveexec_b64 s[46:47], s[40:41]
	s_cbranch_execz .LBB0_438
	v_add_f32_e32 v4, v2, v3
	s_lshl_b32 s10, s9, 2
	v_lshlrev_b64 v[2:3], 7, v[66:67]
	s_ashr_i32 s11, s10, 31
	v_lshl_add_u64 v[2:3], s[0:1], 0, v[2:3]
	v_lshl_add_u64 v[2:3], s[10:11], 2, v[2:3]
	s_lshl_b32 s84, s22, 2
	v_lshl_add_u64 v[2:3], v[2:3], 0, s[84:85]
	global_store_dword v[2:3], v4, off

.LBB0_589:
	v_bfe_u32 v186, v208, 4, 1
	v_mul_u32_u24_e32 v186, 24, v186
	v_mov_b32_e32 v187, 0
	v_lshl_add_u32 v166, s10, 8, v178
	v_lshl_or_b32 v164, s34, 8, v180
	v_ashrrev_i32_e32 v167, 31, v166
	v_lshlrev_b64 v[130:131], 13, v[166:167]
	v_ashrrev_i32_e32 v165, 31, v164
	v_or_b32_e32 v168, 16, v166
	v_lshl_add_u64 v[130:131], s[94:95], 0, v[130:131]
	v_lshlrev_b64 v[132:133], 2, v[164:165]
	v_ashrrev_i32_e32 v169, 31, v168
	v_lshl_add_u64 v[176:177], v[130:131], 0, v[132:133]
	v_lshlrev_b64 v[130:131], 13, v[168:169]
	v_lshl_add_u64 v[130:131], s[94:95], 0, v[130:131]
	v_lshl_add_u64 v[170:171], v[130:131], 0, v[132:133]
	global_load_dwordx4 v[182:185], v[176:177], off
	global_load_dwordx4 v[154:157], v[176:177], off offset:64
	global_load_dwordx4 v[150:153], v[176:177], off offset:512
	global_load_dwordx4 v[146:149], v[176:177], off offset:576
	global_load_dwordx4 v[142:145], v[170:171], off
	global_load_dwordx4 v[138:141], v[170:171], off offset:64
	global_load_dwordx4 v[134:137], v[170:171], off offset:512
	global_load_dwordx4 v[130:133], v[170:171], off offset:576
	v_lshlrev_b64 v[172:173], 11, v[166:167]
	v_lshl_add_u64 v[172:173], v[172:173], 0, v[164:165]
	s_and_b64 vcc, exec, s[50:51]
	v_lshl_add_u64 v[174:175], v[172:173], 1, s[16:17]
	s_waitcnt vmcnt(0)
	v_pk_add_f32 v[128:129], v[128:129], v[184:185]
	v_pk_add_f32 v[126:127], v[126:127], v[182:183]
	global_store_dwordx4 v[176:177], v[126:129], off
	s_cbranch_vccz .LBB0_591
	v_cvt_pk_bf16_f32 v188, v126, v127
	v_cvt_pk_bf16_f32 v189, v128, v129
.LBB0_591:
	v_lshlrev_b64 v[172:173], 11, v[168:169]
	v_pk_add_f32 v[124:125], v[124:125], v[156:157]
	v_pk_add_f32 v[122:123], v[122:123], v[154:155]
	s_and_b64 vcc, exec, s[50:51]
	global_store_dwordx4 v[176:177], v[122:125], off offset:64
	s_cbranch_vccz .LBB0_593
	v_cvt_pk_bf16_f32 v190, v122, v123
	v_cvt_pk_bf16_f32 v191, v124, v125
	s_nop 1
	v_permlane16_swap_b32_e32 v188, v190
	v_permlane16_swap_b32_e32 v189, v191
	v_lshl_add_u64 v[174:175], v[174:175], 0, v[186:187]
	global_store_dwordx4 v[174:175], v[188:191], off
.LBB0_593:
	v_pk_add_f32 v[120:121], v[120:121], v[152:153]
	v_pk_add_f32 v[118:119], v[118:119], v[150:151]
	s_and_b64 vcc, exec, s[50:51]
	global_store_dwordx4 v[176:177], v[118:121], off offset:512
	s_cbranch_vccz .LBB0_595
	v_cvt_pk_bf16_f32 v200, v118, v119
	v_cvt_pk_bf16_f32 v201, v120, v121
.LBB0_595:
	v_pk_add_f32 v[114:115], v[114:115], v[146:147]
	v_cndmask_b32_e64 v146, 0, 1, s[50:51]
	v_pk_add_f32 v[116:117], v[116:117], v[148:149]
	v_cmp_ne_u32_e64 s[44:45], 1, v146
	s_andn2_b64 vcc, exec, s[50:51]
	global_store_dwordx4 v[176:177], v[114:117], off offset:576
	s_cbranch_vccnz .LBB0_599
	v_mul_f32_e32 v127, v127, v127
	v_mul_f32_e32 v123, v123, v123
	v_mul_f32_e32 v119, v119, v119
	v_fmac_f32_e32 v127, v126, v126
	v_mul_f32_e32 v126, v128, v128
	v_fmac_f32_e32 v123, v122, v122
	v_mul_f32_e32 v122, v124, v124
	v_fmac_f32_e32 v119, v118, v118
	v_mul_f32_e32 v118, v120, v120
	v_fmac_f32_e32 v126, v129, v129
	v_fmac_f32_e32 v122, v125, v125
	v_fmac_f32_e32 v118, v121, v121
	v_add_f32_e32 v126, v127, v126
	v_add_f32_e32 v122, v123, v122
	v_add_f32_e32 v118, v119, v118
	v_mul_f32_e32 v119, v115, v115
	v_mul_f32_e32 v120, v117, v117
	v_add_f32_e32 v122, v126, v122
	v_fmac_f32_e32 v119, v114, v114
	v_fmac_f32_e32 v120, v116, v116
	v_add_f32_e32 v118, v122, v118
	v_add_f32_e32 v119, v119, v120
	v_add_f32_e32 v118, v119, v118
	ds_swizzle_b32 v119, v118 offset:swizzle(SWAP,16)
	v_cvt_pk_bf16_f32 v202, v114, v115
	v_cvt_pk_bf16_f32 v203, v116, v117
	s_nop 1
	v_permlane16_swap_b32_e32 v200, v202
	v_permlane16_swap_b32_e32 v201, v203
	global_store_dwordx4 v[174:175], v[200:203], off offset:256
	s_waitcnt lgkmcnt(0)
	v_add_f32_e32 v114, v118, v119
	v_mov_b32_e32 v115, v114
	s_nop 1
	v_permlane32_swap_b32_e32 v114, v115
	s_and_saveexec_b64 s[56:57], s[40:41]
	s_cbranch_execz .LBB0_598
	v_add_f32_e32 v116, v114, v115
	s_lshl_b32 s10, s34, 2
	v_lshlrev_b64 v[114:115], 7, v[166:167]
	s_ashr_i32 s11, s10, 31
	v_lshl_add_u64 v[114:115], s[14:15], 0, v[114:115]
	v_lshl_add_u64 v[114:115], s[10:11], 2, v[114:115]
	s_lshl_b32 s84, s30, 2
	v_lshl_add_u64 v[114:115], v[114:115], 0, s[84:85]
	global_store_dword v[114:115], v116, off

.LBB0_599:
	v_or_b32_e32 v146, 32, v166
	v_ashrrev_i32_e32 v147, 31, v146
	v_lshlrev_b64 v[114:115], 13, v[146:147]
	v_lshl_add_u64 v[114:115], s[94:95], 0, v[114:115]
	v_lshl_add_u64 v[148:149], v[164:165], 2, v[114:115]
	global_load_dwordx4 v[126:129], v[148:149], off
	global_load_dwordx4 v[122:125], v[148:149], off offset:64
	global_load_dwordx4 v[118:121], v[148:149], off offset:512
	global_load_dwordx4 v[114:117], v[148:149], off offset:576
	v_lshl_add_u64 v[150:151], v[172:173], 0, v[164:165]
	v_pk_add_f32 v[112:113], v[112:113], v[144:145]
	v_pk_add_f32 v[110:111], v[110:111], v[142:143]
	s_and_b64 vcc, exec, s[50:51]
	v_lshl_add_u64 v[144:145], v[150:151], 1, s[16:17]
	global_store_dwordx4 v[170:171], v[110:113], off
	s_cbranch_vccz .LBB0_601
	v_cvt_pk_bf16_f32 v188, v110, v111
	v_cvt_pk_bf16_f32 v189, v112, v113
.LBB0_601:
	v_lshlrev_b64 v[142:143], 11, v[146:147]
	v_pk_add_f32 v[108:109], v[108:109], v[140:141]
	v_pk_add_f32 v[106:107], v[106:107], v[138:139]
	s_and_b64 vcc, exec, s[50:51]
	global_store_dwordx4 v[170:171], v[106:109], off offset:64
	s_cbranch_vccz .LBB0_603
	v_cvt_pk_bf16_f32 v190, v106, v107
	v_cvt_pk_bf16_f32 v191, v108, v109
	s_nop 1
	v_permlane16_swap_b32_e32 v188, v190
	v_permlane16_swap_b32_e32 v189, v191
	v_lshl_add_u64 v[144:145], v[144:145], 0, v[186:187]
	global_store_dwordx4 v[144:145], v[188:191], off
.LBB0_603:
	v_pk_add_f32 v[104:105], v[104:105], v[136:137]
	v_pk_add_f32 v[102:103], v[102:103], v[134:135]
	s_and_b64 vcc, exec, s[50:51]
	global_store_dwordx4 v[170:171], v[102:105], off offset:512
	s_cbranch_vccz .LBB0_605
	v_cvt_pk_bf16_f32 v200, v102, v103
	v_cvt_pk_bf16_f32 v201, v104, v105
.LBB0_605:
	v_pk_add_f32 v[100:101], v[100:101], v[132:133]
	v_pk_add_f32 v[98:99], v[98:99], v[130:131]
	s_and_b64 vcc, exec, s[44:45]
	global_store_dwordx4 v[170:171], v[98:101], off offset:576
	s_cbranch_vccnz .LBB0_609
	v_mul_f32_e32 v111, v111, v111
	v_mul_f32_e32 v107, v107, v107
	v_mul_f32_e32 v103, v103, v103
	v_fmac_f32_e32 v111, v110, v110
	v_mul_f32_e32 v110, v112, v112
	v_fmac_f32_e32 v107, v106, v106
	v_mul_f32_e32 v106, v108, v108
	v_fmac_f32_e32 v103, v102, v102
	v_mul_f32_e32 v102, v104, v104
	v_fmac_f32_e32 v110, v113, v113
	v_fmac_f32_e32 v106, v109, v109
	v_fmac_f32_e32 v102, v105, v105
	v_add_f32_e32 v110, v111, v110
	v_add_f32_e32 v106, v107, v106
	v_add_f32_e32 v102, v103, v102
	v_mul_f32_e32 v103, v99, v99
	v_mul_f32_e32 v104, v101, v101
	v_add_f32_e32 v106, v110, v106
	v_fmac_f32_e32 v103, v98, v98
	v_fmac_f32_e32 v104, v100, v100
	v_add_f32_e32 v102, v106, v102
	v_add_f32_e32 v103, v103, v104
	v_add_f32_e32 v102, v103, v102
	ds_swizzle_b32 v103, v102 offset:swizzle(SWAP,16)
	v_cvt_pk_bf16_f32 v202, v98, v99
	v_cvt_pk_bf16_f32 v203, v100, v101
	s_nop 1
	v_permlane16_swap_b32_e32 v200, v202
	v_permlane16_swap_b32_e32 v201, v203
	global_store_dwordx4 v[144:145], v[200:203], off offset:256
	s_waitcnt lgkmcnt(0)
	v_add_f32_e32 v98, v102, v103
	v_mov_b32_e32 v99, v98
	s_nop 1
	v_permlane32_swap_b32_e32 v98, v99
	s_and_saveexec_b64 s[56:57], s[40:41]
	s_cbranch_execz .LBB0_608
	v_add_f32_e32 v100, v98, v99
	s_lshl_b32 s10, s34, 2
	v_lshlrev_b64 v[98:99], 7, v[168:169]
	s_ashr_i32 s11, s10, 31
	v_lshl_add_u64 v[98:99], s[14:15], 0, v[98:99]
	v_lshl_add_u64 v[98:99], s[10:11], 2, v[98:99]
	s_lshl_b32 s84, s30, 2
	v_lshl_add_u64 v[98:99], v[98:99], 0, s[84:85]
	global_store_dword v[98:99], v100, off

.LBB0_609:
	v_or_b32_e32 v130, 48, v166
	v_ashrrev_i32_e32 v131, 31, v130
	v_lshlrev_b64 v[98:99], 13, v[130:131]
	v_lshl_add_u64 v[98:99], s[94:95], 0, v[98:99]
	v_lshl_add_u64 v[132:133], v[164:165], 2, v[98:99]
	global_load_dwordx4 v[110:113], v[132:133], off
	global_load_dwordx4 v[106:109], v[132:133], off offset:64
	global_load_dwordx4 v[102:105], v[132:133], off offset:512
	global_load_dwordx4 v[98:101], v[132:133], off offset:576
	v_lshl_add_u64 v[134:135], v[142:143], 0, v[164:165]
	s_waitcnt vmcnt(11)
	v_pk_add_f32 v[96:97], v[96:97], v[128:129]
	v_pk_add_f32 v[94:95], v[94:95], v[126:127]
	s_and_b64 vcc, exec, s[50:51]
	v_lshl_add_u64 v[128:129], v[134:135], 1, s[16:17]
	global_store_dwordx4 v[148:149], v[94:97], off
	s_cbranch_vccz .LBB0_611
	v_cvt_pk_bf16_f32 v188, v94, v95
	v_cvt_pk_bf16_f32 v189, v96, v97
.LBB0_611:
	v_lshlrev_b64 v[126:127], 11, v[130:131]
	s_waitcnt vmcnt(11)
	v_pk_add_f32 v[92:93], v[92:93], v[124:125]
	v_pk_add_f32 v[90:91], v[90:91], v[122:123]
	s_and_b64 vcc, exec, s[50:51]
	global_store_dwordx4 v[148:149], v[90:93], off offset:64
	s_cbranch_vccz .LBB0_613
	v_cvt_pk_bf16_f32 v190, v90, v91
	v_cvt_pk_bf16_f32 v191, v92, v93
	s_nop 1
	v_permlane16_swap_b32_e32 v188, v190
	v_permlane16_swap_b32_e32 v189, v191
	v_lshl_add_u64 v[128:129], v[128:129], 0, v[186:187]
	global_store_dwordx4 v[128:129], v[188:191], off
.LBB0_613:
	s_waitcnt vmcnt(11)
	v_pk_add_f32 v[88:89], v[88:89], v[120:121]
	v_pk_add_f32 v[86:87], v[86:87], v[118:119]
	s_and_b64 vcc, exec, s[50:51]
	global_store_dwordx4 v[148:149], v[86:89], off offset:512
	s_cbranch_vccz .LBB0_615
	v_cvt_pk_bf16_f32 v200, v86, v87
	v_cvt_pk_bf16_f32 v201, v88, v89
.LBB0_615:
	s_waitcnt vmcnt(11)
	v_pk_add_f32 v[84:85], v[84:85], v[116:117]
	v_pk_add_f32 v[82:83], v[82:83], v[114:115]
	s_and_b64 vcc, exec, s[44:45]
	global_store_dwordx4 v[148:149], v[82:85], off offset:576
	s_cbranch_vccnz .LBB0_619
	v_mul_f32_e32 v95, v95, v95
	v_mul_f32_e32 v91, v91, v91
	v_mul_f32_e32 v87, v87, v87
	v_fmac_f32_e32 v95, v94, v94
	v_mul_f32_e32 v94, v96, v96
	v_fmac_f32_e32 v91, v90, v90
	v_mul_f32_e32 v90, v92, v92
	v_fmac_f32_e32 v87, v86, v86
	v_mul_f32_e32 v86, v88, v88
	v_fmac_f32_e32 v94, v97, v97
	v_fmac_f32_e32 v90, v93, v93
	v_fmac_f32_e32 v86, v89, v89
	v_add_f32_e32 v94, v95, v94
	v_add_f32_e32 v90, v91, v90
	v_add_f32_e32 v86, v87, v86
	v_mul_f32_e32 v87, v83, v83
	v_mul_f32_e32 v88, v85, v85
	v_add_f32_e32 v90, v94, v90
	v_fmac_f32_e32 v87, v82, v82
	v_fmac_f32_e32 v88, v84, v84
	v_add_f32_e32 v86, v90, v86
	v_add_f32_e32 v87, v87, v88
	v_add_f32_e32 v86, v87, v86
	ds_swizzle_b32 v87, v86 offset:swizzle(SWAP,16)
	v_cvt_pk_bf16_f32 v202, v82, v83
	v_cvt_pk_bf16_f32 v203, v84, v85
	s_nop 1
	v_permlane16_swap_b32_e32 v200, v202
	v_permlane16_swap_b32_e32 v201, v203
	global_store_dwordx4 v[128:129], v[200:203], off offset:256
	s_waitcnt lgkmcnt(0)
	v_add_f32_e32 v82, v86, v87
	v_mov_b32_e32 v83, v82
	s_nop 1
	v_permlane32_swap_b32_e32 v82, v83
	s_and_saveexec_b64 s[56:57], s[40:41]
	s_cbranch_execz .LBB0_618
	v_add_f32_e32 v84, v82, v83
	s_lshl_b32 s10, s34, 2
	v_lshlrev_b64 v[82:83], 7, v[146:147]
	s_ashr_i32 s11, s10, 31
	v_lshl_add_u64 v[82:83], s[14:15], 0, v[82:83]
	v_lshl_add_u64 v[82:83], s[10:11], 2, v[82:83]
	s_lshl_b32 s84, s30, 2
	v_lshl_add_u64 v[82:83], v[82:83], 0, s[84:85]
	global_store_dword v[82:83], v84, off

.LBB0_619:
	v_add_u32_e32 v114, 0x80, v166
	v_ashrrev_i32_e32 v115, 31, v114
	v_lshlrev_b64 v[82:83], 13, v[114:115]
	v_lshl_add_u64 v[82:83], s[94:95], 0, v[82:83]
	v_lshl_add_u64 v[116:117], v[164:165], 2, v[82:83]
	global_load_dwordx4 v[94:97], v[116:117], off
	global_load_dwordx4 v[90:93], v[116:117], off offset:64
	global_load_dwordx4 v[86:89], v[116:117], off offset:512
	global_load_dwordx4 v[82:85], v[116:117], off offset:576
	v_lshl_add_u64 v[118:119], v[126:127], 0, v[164:165]
	s_waitcnt vmcnt(11)
	v_pk_add_f32 v[80:81], v[80:81], v[112:113]
	v_pk_add_f32 v[78:79], v[78:79], v[110:111]
	s_and_b64 vcc, exec, s[50:51]
	v_lshl_add_u64 v[112:113], v[118:119], 1, s[16:17]
	global_store_dwordx4 v[132:133], v[78:81], off
	s_cbranch_vccz .LBB0_621
	v_cvt_pk_bf16_f32 v188, v78, v79
	v_cvt_pk_bf16_f32 v189, v80, v81
.LBB0_621:
	v_lshlrev_b64 v[110:111], 11, v[114:115]
	s_waitcnt vmcnt(11)
	v_pk_add_f32 v[76:77], v[76:77], v[108:109]
	v_pk_add_f32 v[74:75], v[74:75], v[106:107]
	s_and_b64 vcc, exec, s[50:51]
	global_store_dwordx4 v[132:133], v[74:77], off offset:64
	s_cbranch_vccz .LBB0_623
	v_cvt_pk_bf16_f32 v190, v74, v75
	v_cvt_pk_bf16_f32 v191, v76, v77
	s_nop 1
	v_permlane16_swap_b32_e32 v188, v190
	v_permlane16_swap_b32_e32 v189, v191
	v_lshl_add_u64 v[112:113], v[112:113], 0, v[186:187]
	global_store_dwordx4 v[112:113], v[188:191], off
.LBB0_623:
	s_waitcnt vmcnt(11)
	v_pk_add_f32 v[72:73], v[72:73], v[104:105]
	v_pk_add_f32 v[70:71], v[70:71], v[102:103]
	s_and_b64 vcc, exec, s[50:51]
	global_store_dwordx4 v[132:133], v[70:73], off offset:512
	s_cbranch_vccz .LBB0_625
	v_cvt_pk_bf16_f32 v200, v70, v71
	v_cvt_pk_bf16_f32 v201, v72, v73
.LBB0_625:
	s_waitcnt vmcnt(11)
	v_pk_add_f32 v[68:69], v[68:69], v[100:101]
	v_pk_add_f32 v[66:67], v[66:67], v[98:99]
	s_and_b64 vcc, exec, s[44:45]
	global_store_dwordx4 v[132:133], v[66:69], off offset:576
	s_cbranch_vccnz .LBB0_629
	v_mul_f32_e32 v79, v79, v79
	v_mul_f32_e32 v75, v75, v75
	v_mul_f32_e32 v71, v71, v71
	v_fmac_f32_e32 v79, v78, v78
	v_mul_f32_e32 v78, v80, v80
	v_fmac_f32_e32 v75, v74, v74
	v_mul_f32_e32 v74, v76, v76
	v_fmac_f32_e32 v71, v70, v70
	v_mul_f32_e32 v70, v72, v72
	v_fmac_f32_e32 v78, v81, v81
	v_fmac_f32_e32 v74, v77, v77
	v_fmac_f32_e32 v70, v73, v73
	v_add_f32_e32 v78, v79, v78
	v_add_f32_e32 v74, v75, v74
	v_add_f32_e32 v70, v71, v70
	v_mul_f32_e32 v71, v67, v67
	v_mul_f32_e32 v72, v69, v69
	v_add_f32_e32 v74, v78, v74
	v_fmac_f32_e32 v71, v66, v66
	v_fmac_f32_e32 v72, v68, v68
	v_add_f32_e32 v70, v74, v70
	v_add_f32_e32 v71, v71, v72
	v_add_f32_e32 v70, v71, v70
	ds_swizzle_b32 v71, v70 offset:swizzle(SWAP,16)
	v_cvt_pk_bf16_f32 v202, v66, v67
	v_cvt_pk_bf16_f32 v203, v68, v69
	s_nop 1
	v_permlane16_swap_b32_e32 v200, v202
	v_permlane16_swap_b32_e32 v201, v203
	global_store_dwordx4 v[112:113], v[200:203], off offset:256
	s_waitcnt lgkmcnt(0)
	v_add_f32_e32 v66, v70, v71
	v_mov_b32_e32 v67, v66
	s_nop 1
	v_permlane32_swap_b32_e32 v66, v67
	s_and_saveexec_b64 s[56:57], s[40:41]
	s_cbranch_execz .LBB0_628
	v_add_f32_e32 v68, v66, v67
	s_lshl_b32 s10, s34, 2
	v_lshlrev_b64 v[66:67], 7, v[130:131]
	s_ashr_i32 s11, s10, 31
	v_lshl_add_u64 v[66:67], s[14:15], 0, v[66:67]
	v_lshl_add_u64 v[66:67], s[10:11], 2, v[66:67]
	s_lshl_b32 s84, s30, 2
	v_lshl_add_u64 v[66:67], v[66:67], 0, s[84:85]
	global_store_dword v[66:67], v68, off

.LBB0_629:
	v_or_b32_e32 v98, 16, v114
	v_ashrrev_i32_e32 v99, 31, v98
	v_lshlrev_b64 v[66:67], 13, v[98:99]
	v_lshl_add_u64 v[66:67], s[94:95], 0, v[66:67]
	v_lshl_add_u64 v[100:101], v[164:165], 2, v[66:67]
	global_load_dwordx4 v[78:81], v[100:101], off
	global_load_dwordx4 v[74:77], v[100:101], off offset:64
	global_load_dwordx4 v[70:73], v[100:101], off offset:512
	global_load_dwordx4 v[66:69], v[100:101], off offset:576
	v_lshl_add_u64 v[102:103], v[110:111], 0, v[164:165]
	s_waitcnt vmcnt(11)
	v_pk_add_f32 v[64:65], v[64:65], v[96:97]
	v_pk_add_f32 v[62:63], v[62:63], v[94:95]
	s_and_b64 vcc, exec, s[50:51]
	v_lshl_add_u64 v[96:97], v[102:103], 1, s[16:17]
	global_store_dwordx4 v[116:117], v[62:65], off
	s_cbranch_vccz .LBB0_631
	v_cvt_pk_bf16_f32 v188, v62, v63
	v_cvt_pk_bf16_f32 v189, v64, v65
.LBB0_631:
	v_lshlrev_b64 v[94:95], 11, v[98:99]
	s_waitcnt vmcnt(11)
	v_pk_add_f32 v[60:61], v[60:61], v[92:93]
	v_pk_add_f32 v[58:59], v[58:59], v[90:91]
	s_and_b64 vcc, exec, s[50:51]
	global_store_dwordx4 v[116:117], v[58:61], off offset:64
	s_cbranch_vccz .LBB0_633
	v_cvt_pk_bf16_f32 v190, v58, v59
	v_cvt_pk_bf16_f32 v191, v60, v61
	s_nop 1
	v_permlane16_swap_b32_e32 v188, v190
	v_permlane16_swap_b32_e32 v189, v191
	v_lshl_add_u64 v[96:97], v[96:97], 0, v[186:187]
	global_store_dwordx4 v[96:97], v[188:191], off
.LBB0_633:
	s_waitcnt vmcnt(11)
	v_pk_add_f32 v[56:57], v[56:57], v[88:89]
	v_pk_add_f32 v[54:55], v[54:55], v[86:87]
	s_and_b64 vcc, exec, s[50:51]
	global_store_dwordx4 v[116:117], v[54:57], off offset:512
	s_cbranch_vccz .LBB0_635
	v_cvt_pk_bf16_f32 v200, v54, v55
	v_cvt_pk_bf16_f32 v201, v56, v57
.LBB0_635:
	s_waitcnt vmcnt(11)
	v_pk_add_f32 v[52:53], v[52:53], v[84:85]
	v_pk_add_f32 v[50:51], v[50:51], v[82:83]
	s_and_b64 vcc, exec, s[44:45]
	global_store_dwordx4 v[116:117], v[50:53], off offset:576
	s_cbranch_vccnz .LBB0_639
	v_mul_f32_e32 v63, v63, v63
	v_mul_f32_e32 v59, v59, v59
	v_mul_f32_e32 v55, v55, v55
	v_fmac_f32_e32 v63, v62, v62
	v_mul_f32_e32 v62, v64, v64
	v_fmac_f32_e32 v59, v58, v58
	v_mul_f32_e32 v58, v60, v60
	v_fmac_f32_e32 v55, v54, v54
	v_mul_f32_e32 v54, v56, v56
	v_fmac_f32_e32 v62, v65, v65
	v_fmac_f32_e32 v58, v61, v61
	v_fmac_f32_e32 v54, v57, v57
	v_add_f32_e32 v62, v63, v62
	v_add_f32_e32 v58, v59, v58
	v_add_f32_e32 v54, v55, v54
	v_mul_f32_e32 v55, v51, v51
	v_mul_f32_e32 v56, v53, v53
	v_add_f32_e32 v58, v62, v58
	v_fmac_f32_e32 v55, v50, v50
	v_fmac_f32_e32 v56, v52, v52
	v_add_f32_e32 v54, v58, v54
	v_add_f32_e32 v55, v55, v56
	v_add_f32_e32 v54, v55, v54
	ds_swizzle_b32 v55, v54 offset:swizzle(SWAP,16)
	v_cvt_pk_bf16_f32 v202, v50, v51
	v_cvt_pk_bf16_f32 v203, v52, v53
	s_nop 1
	v_permlane16_swap_b32_e32 v200, v202
	v_permlane16_swap_b32_e32 v201, v203
	global_store_dwordx4 v[96:97], v[200:203], off offset:256
	s_waitcnt lgkmcnt(0)
	v_add_f32_e32 v50, v54, v55
	v_mov_b32_e32 v51, v50
	s_nop 1
	v_permlane32_swap_b32_e32 v50, v51
	s_and_saveexec_b64 s[56:57], s[40:41]
	s_cbranch_execz .LBB0_638
	v_add_f32_e32 v52, v50, v51
	s_lshl_b32 s10, s34, 2
	v_lshlrev_b64 v[50:51], 7, v[114:115]
	s_ashr_i32 s11, s10, 31
	v_lshl_add_u64 v[50:51], s[14:15], 0, v[50:51]
	v_lshl_add_u64 v[50:51], s[10:11], 2, v[50:51]
	s_lshl_b32 s84, s30, 2
	v_lshl_add_u64 v[50:51], v[50:51], 0, s[84:85]
	global_store_dword v[50:51], v52, off

.LBB0_639:
	v_or_b32_e32 v82, 32, v114
	v_ashrrev_i32_e32 v83, 31, v82
	v_lshlrev_b64 v[50:51], 13, v[82:83]
	v_lshl_add_u64 v[50:51], s[94:95], 0, v[50:51]
	v_lshl_add_u64 v[84:85], v[164:165], 2, v[50:51]
	global_load_dwordx4 v[62:65], v[84:85], off
	global_load_dwordx4 v[58:61], v[84:85], off offset:64
	global_load_dwordx4 v[54:57], v[84:85], off offset:512
	global_load_dwordx4 v[50:53], v[84:85], off offset:576
	v_lshl_add_u64 v[86:87], v[94:95], 0, v[164:165]
	s_waitcnt vmcnt(11)
	v_pk_add_f32 v[48:49], v[48:49], v[80:81]
	v_pk_add_f32 v[46:47], v[46:47], v[78:79]
	s_and_b64 vcc, exec, s[50:51]
	v_lshl_add_u64 v[80:81], v[86:87], 1, s[16:17]
	global_store_dwordx4 v[100:101], v[46:49], off
	s_cbranch_vccz .LBB0_641
	v_cvt_pk_bf16_f32 v188, v46, v47
	v_cvt_pk_bf16_f32 v189, v48, v49
.LBB0_641:
	v_lshlrev_b64 v[78:79], 11, v[82:83]
	s_waitcnt vmcnt(11)
	v_pk_add_f32 v[44:45], v[44:45], v[76:77]
	v_pk_add_f32 v[42:43], v[42:43], v[74:75]
	s_and_b64 vcc, exec, s[50:51]
	global_store_dwordx4 v[100:101], v[42:45], off offset:64
	s_cbranch_vccz .LBB0_643
	v_cvt_pk_bf16_f32 v190, v42, v43
	v_cvt_pk_bf16_f32 v191, v44, v45
	s_nop 1
	v_permlane16_swap_b32_e32 v188, v190
	v_permlane16_swap_b32_e32 v189, v191
	v_lshl_add_u64 v[80:81], v[80:81], 0, v[186:187]
	global_store_dwordx4 v[80:81], v[188:191], off
.LBB0_643:
	s_waitcnt vmcnt(11)
	v_pk_add_f32 v[40:41], v[40:41], v[72:73]
	v_pk_add_f32 v[38:39], v[38:39], v[70:71]
	s_and_b64 vcc, exec, s[50:51]
	global_store_dwordx4 v[100:101], v[38:41], off offset:512
	s_cbranch_vccz .LBB0_645
	v_cvt_pk_bf16_f32 v200, v38, v39
	v_cvt_pk_bf16_f32 v201, v40, v41
.LBB0_645:
	s_waitcnt vmcnt(11)
	v_pk_add_f32 v[36:37], v[36:37], v[68:69]
	v_pk_add_f32 v[34:35], v[34:35], v[66:67]
	s_and_b64 vcc, exec, s[44:45]
	global_store_dwordx4 v[100:101], v[34:37], off offset:576
	s_cbranch_vccnz .LBB0_649
	v_mul_f32_e32 v47, v47, v47
	v_mul_f32_e32 v43, v43, v43
	v_mul_f32_e32 v39, v39, v39
	v_fmac_f32_e32 v47, v46, v46
	v_mul_f32_e32 v46, v48, v48
	v_fmac_f32_e32 v43, v42, v42
	v_mul_f32_e32 v42, v44, v44
	v_fmac_f32_e32 v39, v38, v38
	v_mul_f32_e32 v38, v40, v40
	v_fmac_f32_e32 v46, v49, v49
	v_fmac_f32_e32 v42, v45, v45
	v_fmac_f32_e32 v38, v41, v41
	v_add_f32_e32 v46, v47, v46
	v_add_f32_e32 v42, v43, v42
	v_add_f32_e32 v38, v39, v38
	v_mul_f32_e32 v39, v35, v35
	v_mul_f32_e32 v40, v37, v37
	v_add_f32_e32 v42, v46, v42
	v_fmac_f32_e32 v39, v34, v34
	v_fmac_f32_e32 v40, v36, v36
	v_add_f32_e32 v38, v42, v38
	v_add_f32_e32 v39, v39, v40
	v_add_f32_e32 v38, v39, v38
	ds_swizzle_b32 v39, v38 offset:swizzle(SWAP,16)
	v_cvt_pk_bf16_f32 v202, v34, v35
	v_cvt_pk_bf16_f32 v203, v36, v37
	s_nop 1
	v_permlane16_swap_b32_e32 v200, v202
	v_permlane16_swap_b32_e32 v201, v203
	global_store_dwordx4 v[80:81], v[200:203], off offset:256
	s_waitcnt lgkmcnt(0)
	v_add_f32_e32 v34, v38, v39
	v_mov_b32_e32 v35, v34
	s_nop 1
	v_permlane32_swap_b32_e32 v34, v35
	s_and_saveexec_b64 s[56:57], s[40:41]
	s_cbranch_execz .LBB0_648
	v_add_f32_e32 v36, v34, v35
	s_lshl_b32 s10, s34, 2
	v_lshlrev_b64 v[34:35], 7, v[98:99]
	s_ashr_i32 s11, s10, 31
	v_lshl_add_u64 v[34:35], s[14:15], 0, v[34:35]
	v_lshl_add_u64 v[34:35], s[10:11], 2, v[34:35]
	s_lshl_b32 s84, s30, 2
	v_lshl_add_u64 v[34:35], v[34:35], 0, s[84:85]
	global_store_dword v[34:35], v36, off

.LBB0_649:
	v_or_b32_e32 v66, 48, v114
	v_ashrrev_i32_e32 v67, 31, v66
	v_lshlrev_b64 v[34:35], 13, v[66:67]
	v_lshl_add_u64 v[34:35], s[94:95], 0, v[34:35]
	v_lshl_add_u64 v[68:69], v[164:165], 2, v[34:35]
	global_load_dwordx4 v[46:49], v[68:69], off
	global_load_dwordx4 v[42:45], v[68:69], off offset:64
	global_load_dwordx4 v[38:41], v[68:69], off offset:512
	global_load_dwordx4 v[34:37], v[68:69], off offset:576
	v_lshl_add_u64 v[70:71], v[78:79], 0, v[164:165]
	s_waitcnt vmcnt(11)
	v_pk_add_f32 v[32:33], v[32:33], v[64:65]
	v_pk_add_f32 v[30:31], v[30:31], v[62:63]
	s_and_b64 vcc, exec, s[50:51]
	v_lshl_add_u64 v[64:65], v[70:71], 1, s[16:17]
	global_store_dwordx4 v[84:85], v[30:33], off
	s_cbranch_vccz .LBB0_651
	v_cvt_pk_bf16_f32 v188, v30, v31
	v_cvt_pk_bf16_f32 v189, v32, v33
.LBB0_651:
	v_lshlrev_b64 v[62:63], 11, v[66:67]
	s_waitcnt vmcnt(11)
	v_pk_add_f32 v[28:29], v[28:29], v[60:61]
	v_pk_add_f32 v[26:27], v[26:27], v[58:59]
	s_and_b64 vcc, exec, s[50:51]
	global_store_dwordx4 v[84:85], v[26:29], off offset:64
	s_cbranch_vccz .LBB0_653
	v_cvt_pk_bf16_f32 v190, v26, v27
	v_cvt_pk_bf16_f32 v191, v28, v29
	s_nop 1
	v_permlane16_swap_b32_e32 v188, v190
	v_permlane16_swap_b32_e32 v189, v191
	v_lshl_add_u64 v[64:65], v[64:65], 0, v[186:187]
	global_store_dwordx4 v[64:65], v[188:191], off
.LBB0_653:
	s_waitcnt vmcnt(11)
	v_pk_add_f32 v[24:25], v[24:25], v[56:57]
	v_pk_add_f32 v[22:23], v[22:23], v[54:55]
	s_and_b64 vcc, exec, s[50:51]
	global_store_dwordx4 v[84:85], v[22:25], off offset:512
	s_cbranch_vccz .LBB0_655
	v_cvt_pk_bf16_f32 v200, v22, v23
	v_cvt_pk_bf16_f32 v201, v24, v25
.LBB0_655:
	s_waitcnt vmcnt(11)
	v_pk_add_f32 v[20:21], v[20:21], v[52:53]
	v_pk_add_f32 v[18:19], v[18:19], v[50:51]
	s_and_b64 vcc, exec, s[44:45]
	global_store_dwordx4 v[84:85], v[18:21], off offset:576
	s_cbranch_vccnz .LBB0_659
	v_mul_f32_e32 v31, v31, v31
	v_mul_f32_e32 v27, v27, v27
	v_mul_f32_e32 v23, v23, v23
	v_fmac_f32_e32 v31, v30, v30
	v_mul_f32_e32 v30, v32, v32
	v_fmac_f32_e32 v27, v26, v26
	v_mul_f32_e32 v26, v28, v28
	v_fmac_f32_e32 v23, v22, v22
	v_mul_f32_e32 v22, v24, v24
	v_fmac_f32_e32 v30, v33, v33
	v_fmac_f32_e32 v26, v29, v29
	v_fmac_f32_e32 v22, v25, v25
	v_add_f32_e32 v30, v31, v30
	v_add_f32_e32 v26, v27, v26
	v_add_f32_e32 v22, v23, v22
	v_mul_f32_e32 v23, v19, v19
	v_mul_f32_e32 v24, v21, v21
	v_add_f32_e32 v26, v30, v26
	v_fmac_f32_e32 v23, v18, v18
	v_fmac_f32_e32 v24, v20, v20
	v_add_f32_e32 v22, v26, v22
	v_add_f32_e32 v23, v23, v24
	v_add_f32_e32 v22, v23, v22
	ds_swizzle_b32 v23, v22 offset:swizzle(SWAP,16)
	v_cvt_pk_bf16_f32 v202, v18, v19
	v_cvt_pk_bf16_f32 v203, v20, v21
	s_nop 1
	v_permlane16_swap_b32_e32 v200, v202
	v_permlane16_swap_b32_e32 v201, v203
	global_store_dwordx4 v[64:65], v[200:203], off offset:256
	s_waitcnt lgkmcnt(0)
	v_add_f32_e32 v18, v22, v23
	v_mov_b32_e32 v19, v18
	s_nop 1
	v_permlane32_swap_b32_e32 v18, v19
	s_and_saveexec_b64 s[56:57], s[40:41]
	s_cbranch_execz .LBB0_658
	v_add_f32_e32 v20, v18, v19
	s_lshl_b32 s10, s34, 2
	v_lshlrev_b64 v[18:19], 7, v[82:83]
	s_ashr_i32 s11, s10, 31
	v_lshl_add_u64 v[18:19], s[14:15], 0, v[18:19]
	v_lshl_add_u64 v[18:19], s[10:11], 2, v[18:19]
	s_lshl_b32 s84, s30, 2
	v_lshl_add_u64 v[18:19], v[18:19], 0, s[84:85]
	global_store_dword v[18:19], v20, off

.LBB0_659:
	s_nop 0
	v_lshl_add_u64 v[18:19], v[62:63], 0, v[164:165]
	s_waitcnt vmcnt(7)
	v_pk_add_f32 v[16:17], v[16:17], v[48:49]
	v_pk_add_f32 v[14:15], v[14:15], v[46:47]
	s_and_b64 vcc, exec, s[50:51]
	v_lshl_add_u64 v[18:19], v[18:19], 1, s[16:17]
	global_store_dwordx4 v[68:69], v[14:17], off
	s_cbranch_vccz .LBB0_661
	v_cvt_pk_bf16_f32 v188, v14, v15
	v_cvt_pk_bf16_f32 v189, v16, v17
.LBB0_661:
	s_waitcnt vmcnt(7)
	v_pk_add_f32 v[12:13], v[12:13], v[44:45]
	v_pk_add_f32 v[10:11], v[10:11], v[42:43]
	s_and_b64 vcc, exec, s[50:51]
	global_store_dwordx4 v[68:69], v[10:13], off offset:64
	s_cbranch_vccz .LBB0_663
	v_cvt_pk_bf16_f32 v190, v10, v11
	v_cvt_pk_bf16_f32 v191, v12, v13
	s_nop 1
	v_permlane16_swap_b32_e32 v188, v190
	v_permlane16_swap_b32_e32 v189, v191
	v_lshl_add_u64 v[18:19], v[18:19], 0, v[186:187]
	global_store_dwordx4 v[18:19], v[188:191], off
.LBB0_663:
	s_waitcnt vmcnt(7)
	v_pk_add_f32 v[8:9], v[8:9], v[40:41]
	v_pk_add_f32 v[6:7], v[6:7], v[38:39]
	s_and_b64 vcc, exec, s[50:51]
	global_store_dwordx4 v[68:69], v[6:9], off offset:512
	s_cbranch_vccz .LBB0_665
	v_cvt_pk_bf16_f32 v200, v6, v7
	v_cvt_pk_bf16_f32 v201, v8, v9
.LBB0_665:
	s_waitcnt vmcnt(7)
	v_pk_add_f32 v[4:5], v[4:5], v[36:37]
	v_pk_add_f32 v[2:3], v[2:3], v[34:35]
	s_and_b64 vcc, exec, s[44:45]
	global_store_dwordx4 v[68:69], v[2:5], off offset:576
	s_cbranch_vccnz .LBB0_669
	v_mul_f32_e32 v15, v15, v15
	v_mul_f32_e32 v11, v11, v11
	v_mul_f32_e32 v7, v7, v7
	v_fmac_f32_e32 v15, v14, v14
	v_mul_f32_e32 v14, v16, v16
	v_fmac_f32_e32 v11, v10, v10
	v_mul_f32_e32 v10, v12, v12
	v_fmac_f32_e32 v7, v6, v6
	v_mul_f32_e32 v6, v8, v8
	v_fmac_f32_e32 v14, v17, v17
	v_fmac_f32_e32 v10, v13, v13
	v_fmac_f32_e32 v6, v9, v9
	v_add_f32_e32 v14, v15, v14
	v_add_f32_e32 v10, v11, v10
	v_add_f32_e32 v6, v7, v6
	v_mul_f32_e32 v7, v3, v3
	v_mul_f32_e32 v8, v5, v5
	v_add_f32_e32 v10, v14, v10
	v_fmac_f32_e32 v7, v2, v2
	v_fmac_f32_e32 v8, v4, v4
	v_add_f32_e32 v6, v10, v6
	v_add_f32_e32 v7, v7, v8
	v_add_f32_e32 v6, v7, v6
	ds_swizzle_b32 v7, v6 offset:swizzle(SWAP,16)
	v_cvt_pk_bf16_f32 v202, v2, v3
	v_cvt_pk_bf16_f32 v203, v4, v5
	s_nop 1
	v_permlane16_swap_b32_e32 v200, v202
	v_permlane16_swap_b32_e32 v201, v203
	global_store_dwordx4 v[18:19], v[200:203], off offset:256
	s_waitcnt lgkmcnt(0)
	v_add_f32_e32 v2, v6, v7
	v_mov_b32_e32 v3, v2
	s_nop 1
	v_permlane32_swap_b32_e32 v2, v3
	s_and_saveexec_b64 s[44:45], s[40:41]
	s_cbranch_execz .LBB0_668
	v_add_f32_e32 v4, v2, v3
	s_lshl_b32 s10, s34, 2
	v_lshlrev_b64 v[2:3], 7, v[66:67]
	s_ashr_i32 s11, s10, 31
	v_lshl_add_u64 v[2:3], s[14:15], 0, v[2:3]
	v_lshl_add_u64 v[2:3], s[10:11], 2, v[2:3]
	s_lshl_b32 s84, s30, 2
	v_lshl_add_u64 v[2:3], v[2:3], 0, s[84:85]
	global_store_dword v[2:3], v4, off
